# mlp1 relu^2 epilogue: 128 redundant v_max x,x,x canonicalizes dropped (v_max 0,x already quiets), store-data hazard nops re-placed; on top of the pk-math PC1 epilogue
# speedup vs baseline: 1.0072x; 1.0016x over previous
.LBB0_1769:
	v_mov_b32_e32 v141, v143
	v_mov_b32_e32 v140, v142
	s_lshl_b32 s23, s61, 8
	s_add_i32 s23, s23, s56
	v_add_u32_e32 v140, s23, v140
	s_lshl_b32 s30, s60, 8
	v_lshlrev_b32_e32 v146, 3, v141
	v_ashrrev_i32_e32 v141, 31, v140
	v_max_f32_e32 v124, 0, v124
	v_max_f32_e32 v120, 0, v120
	v_max_f32_e32 v125, 0, v125
	v_max_f32_e32 v121, 0, v121
	s_ashr_i32 s31, s30, 31
	v_lshlrev_b64 v[148:149], 13, v[140:141]
	v_max_f32_e32 v122, 0, v122
	v_max_f32_e32 v123, 0, v123
	v_pk_mul_f32 v[124:125], v[124:125], v[124:125]
	v_pk_mul_f32 v[120:121], v[120:121], v[120:121]
	v_max_f32_e32 v126, 0, v126
	v_max_f32_e32 v127, 0, v127
	v_pk_mul_f32 v[150:151], v[122:123], v[122:123]
	v_cvt_pk_bf16_f32 v122, v124, v125
	v_cvt_pk_bf16_f32 v124, v120, v121
	v_lshl_add_u64 v[120:121], s[20:21], 0, v[148:149]
	s_lshl_b64 s[30:31], s[30:31], 1
	v_ashrrev_i32_e32 v147, 31, v146
	v_pk_mul_f32 v[126:127], v[126:127], v[126:127]
	v_lshl_add_u64 v[120:121], v[120:121], 0, s[30:31]
	v_cvt_pk_bf16_f32 v123, v126, v127
	v_lshl_add_u64 v[126:127], v[120:121], 0, s[68:69]
	v_lshlrev_b64 v[120:121], 1, v[146:147]
	v_max_f32_e32 v116, 0, v116
	v_max_f32_e32 v117, 0, v117
	v_cvt_pk_bf16_f32 v125, v150, v151
	v_lshl_add_u64 v[126:127], v[126:127], 0, v[120:121]
	v_max_f32_e32 v112, 0, v112
	v_max_f32_e32 v113, 0, v113
	v_max_f32_e32 v114, 0, v114
	v_max_f32_e32 v115, 0, v115
	v_pk_mul_f32 v[116:117], v[116:117], v[116:117]
	global_store_dwordx4 v[126:127], v[122:125], off
	s_nop 1
	v_pk_mul_f32 v[122:123], v[114:115], v[114:115]
	v_pk_mul_f32 v[114:115], v[112:113], v[112:113]
	v_cvt_pk_bf16_f32 v112, v116, v117
	v_lshl_add_u64 v[116:117], s[14:15], 0, v[148:149]
	v_lshl_add_u64 v[116:117], v[116:117], 0, s[30:31]
	v_lshl_add_u64 v[116:117], v[116:117], 0, s[68:69]
	v_max_f32_e32 v118, 0, v118
	v_max_f32_e32 v119, 0, v119
	v_lshl_add_u64 v[116:117], v[116:117], 0, v[120:121]
	v_pk_mul_f32 v[118:119], v[118:119], v[118:119]
	v_add_co_u32_e32 v116, vcc, s11, v116
	v_cvt_pk_bf16_f32 v113, v118, v119
	v_cvt_pk_bf16_f32 v114, v114, v115
	v_cvt_pk_bf16_f32 v115, v122, v123
	v_addc_co_u32_e32 v117, vcc, 0, v117, vcc
	global_store_dwordx4 v[116:117], v[112:115], off offset:256
	s_nop 1
	v_add_u32_e32 v112, 16, v140
	v_ashrrev_i32_e32 v113, 31, v112
	v_max_f32_e32 v108, 0, v108
	v_max_f32_e32 v109, 0, v109
	v_lshlrev_b64 v[112:113], 13, v[112:113]
	v_max_f32_e32 v104, 0, v104
	v_max_f32_e32 v105, 0, v105
	v_max_f32_e32 v106, 0, v106
	v_max_f32_e32 v107, 0, v107
	v_pk_mul_f32 v[108:109], v[108:109], v[108:109]
	v_pk_mul_f32 v[114:115], v[106:107], v[106:107]
	v_pk_mul_f32 v[106:107], v[104:105], v[104:105]
	v_cvt_pk_bf16_f32 v104, v108, v109
	v_lshl_add_u64 v[108:109], s[20:21], 0, v[112:113]
	v_max_f32_e32 v110, 0, v110
	v_max_f32_e32 v111, 0, v111
	v_lshl_add_u64 v[108:109], v[108:109], 0, s[30:31]
	v_pk_mul_f32 v[110:111], v[110:111], v[110:111]
	v_lshl_add_u64 v[108:109], v[108:109], 0, s[68:69]
	v_max_f32_e32 v100, 0, v100
	v_max_f32_e32 v101, 0, v101
	v_cvt_pk_bf16_f32 v105, v110, v111
	v_cvt_pk_bf16_f32 v106, v106, v107
	v_cvt_pk_bf16_f32 v107, v114, v115
	v_lshl_add_u64 v[108:109], v[108:109], 0, v[120:121]
	v_max_f32_e32 v96, 0, v96
	v_max_f32_e32 v97, 0, v97
	v_max_f32_e32 v98, 0, v98
	v_max_f32_e32 v99, 0, v99
	v_pk_mul_f32 v[100:101], v[100:101], v[100:101]
	global_store_dwordx4 v[108:109], v[104:107], off
	s_nop 1
	v_pk_mul_f32 v[104:105], v[98:99], v[98:99]
	v_pk_mul_f32 v[98:99], v[96:97], v[96:97]
	v_cvt_pk_bf16_f32 v96, v100, v101
	v_lshl_add_u64 v[100:101], s[14:15], 0, v[112:113]
	v_lshl_add_u64 v[100:101], v[100:101], 0, s[30:31]
	v_lshl_add_u64 v[100:101], v[100:101], 0, s[68:69]
	v_max_f32_e32 v102, 0, v102
	v_max_f32_e32 v103, 0, v103
	v_lshl_add_u64 v[100:101], v[100:101], 0, v[120:121]
	v_pk_mul_f32 v[102:103], v[102:103], v[102:103]
	v_add_co_u32_e32 v100, vcc, s11, v100
	v_cvt_pk_bf16_f32 v97, v102, v103
	v_cvt_pk_bf16_f32 v98, v98, v99
	v_cvt_pk_bf16_f32 v99, v104, v105
	v_addc_co_u32_e32 v101, vcc, 0, v101, vcc
	global_store_dwordx4 v[100:101], v[96:99], off offset:256
	s_nop 1
	v_add_u32_e32 v96, 32, v140
	v_ashrrev_i32_e32 v97, 31, v96
	v_max_f32_e32 v92, 0, v92
	v_max_f32_e32 v93, 0, v93
	v_lshlrev_b64 v[96:97], 13, v[96:97]
	v_max_f32_e32 v88, 0, v88
	v_max_f32_e32 v89, 0, v89
	v_max_f32_e32 v90, 0, v90
	v_max_f32_e32 v91, 0, v91
	v_pk_mul_f32 v[92:93], v[92:93], v[92:93]
	v_pk_mul_f32 v[98:99], v[90:91], v[90:91]
	v_pk_mul_f32 v[90:91], v[88:89], v[88:89]
	v_cvt_pk_bf16_f32 v88, v92, v93
	v_lshl_add_u64 v[92:93], s[20:21], 0, v[96:97]
	v_max_f32_e32 v94, 0, v94
	v_max_f32_e32 v95, 0, v95
	v_lshl_add_u64 v[92:93], v[92:93], 0, s[30:31]
	v_pk_mul_f32 v[94:95], v[94:95], v[94:95]
	v_lshl_add_u64 v[92:93], v[92:93], 0, s[68:69]
	v_max_f32_e32 v84, 0, v84
	v_max_f32_e32 v85, 0, v85
	v_cvt_pk_bf16_f32 v89, v94, v95
	v_cvt_pk_bf16_f32 v90, v90, v91
	v_cvt_pk_bf16_f32 v91, v98, v99
	v_lshl_add_u64 v[92:93], v[92:93], 0, v[120:121]
	v_max_f32_e32 v80, 0, v80
	v_max_f32_e32 v81, 0, v81
	v_max_f32_e32 v82, 0, v82
	v_max_f32_e32 v83, 0, v83
	v_pk_mul_f32 v[84:85], v[84:85], v[84:85]
	global_store_dwordx4 v[92:93], v[88:91], off
	s_nop 1
	v_pk_mul_f32 v[88:89], v[82:83], v[82:83]
	v_pk_mul_f32 v[82:83], v[80:81], v[80:81]
	v_cvt_pk_bf16_f32 v80, v84, v85
	v_lshl_add_u64 v[84:85], s[14:15], 0, v[96:97]
	v_lshl_add_u64 v[84:85], v[84:85], 0, s[30:31]
	v_lshl_add_u64 v[84:85], v[84:85], 0, s[68:69]
	v_max_f32_e32 v86, 0, v86
	v_max_f32_e32 v87, 0, v87
	v_lshl_add_u64 v[84:85], v[84:85], 0, v[120:121]
	v_pk_mul_f32 v[86:87], v[86:87], v[86:87]
	v_add_co_u32_e32 v84, vcc, s11, v84
	v_cvt_pk_bf16_f32 v81, v86, v87
	v_cvt_pk_bf16_f32 v82, v82, v83
	v_cvt_pk_bf16_f32 v83, v88, v89
	v_addc_co_u32_e32 v85, vcc, 0, v85, vcc
	global_store_dwordx4 v[84:85], v[80:83], off offset:256
	s_nop 1
	v_add_u32_e32 v80, 48, v140
	v_ashrrev_i32_e32 v81, 31, v80
	v_max_f32_e32 v76, 0, v76
	v_max_f32_e32 v77, 0, v77
	v_lshlrev_b64 v[80:81], 13, v[80:81]
	v_max_f32_e32 v72, 0, v72
	v_max_f32_e32 v73, 0, v73
	v_max_f32_e32 v74, 0, v74
	v_max_f32_e32 v75, 0, v75
	v_pk_mul_f32 v[76:77], v[76:77], v[76:77]
	v_pk_mul_f32 v[82:83], v[74:75], v[74:75]
	v_pk_mul_f32 v[74:75], v[72:73], v[72:73]
	v_cvt_pk_bf16_f32 v72, v76, v77
	v_lshl_add_u64 v[76:77], s[20:21], 0, v[80:81]
	v_max_f32_e32 v78, 0, v78
	v_max_f32_e32 v79, 0, v79
	v_lshl_add_u64 v[76:77], v[76:77], 0, s[30:31]
	v_pk_mul_f32 v[78:79], v[78:79], v[78:79]
	v_lshl_add_u64 v[76:77], v[76:77], 0, s[68:69]
	v_max_f32_e32 v68, 0, v68
	v_max_f32_e32 v69, 0, v69
	v_cvt_pk_bf16_f32 v73, v78, v79
	v_cvt_pk_bf16_f32 v74, v74, v75
	v_cvt_pk_bf16_f32 v75, v82, v83
	v_lshl_add_u64 v[76:77], v[76:77], 0, v[120:121]
	v_max_f32_e32 v64, 0, v64
	v_max_f32_e32 v65, 0, v65
	v_max_f32_e32 v66, 0, v66
	v_max_f32_e32 v67, 0, v67
	v_pk_mul_f32 v[68:69], v[68:69], v[68:69]
	global_store_dwordx4 v[76:77], v[72:75], off
	s_nop 1
	v_pk_mul_f32 v[72:73], v[66:67], v[66:67]
	v_pk_mul_f32 v[66:67], v[64:65], v[64:65]
	v_cvt_pk_bf16_f32 v64, v68, v69
	v_lshl_add_u64 v[68:69], s[14:15], 0, v[80:81]
	v_lshl_add_u64 v[68:69], v[68:69], 0, s[30:31]
	v_lshl_add_u64 v[68:69], v[68:69], 0, s[68:69]
	v_max_f32_e32 v70, 0, v70
	v_max_f32_e32 v71, 0, v71
	v_lshl_add_u64 v[68:69], v[68:69], 0, v[120:121]
	v_pk_mul_f32 v[70:71], v[70:71], v[70:71]
	v_add_co_u32_e32 v68, vcc, s11, v68
	v_cvt_pk_bf16_f32 v65, v70, v71
	v_cvt_pk_bf16_f32 v66, v66, v67
	v_cvt_pk_bf16_f32 v67, v72, v73
	v_addc_co_u32_e32 v69, vcc, 0, v69, vcc
	global_store_dwordx4 v[68:69], v[64:67], off offset:256
	s_nop 1
	v_add_u32_e32 v64, 0x80, v140
	v_ashrrev_i32_e32 v65, 31, v64
	v_max_f32_e32 v60, 0, v60
	v_max_f32_e32 v61, 0, v61
	v_lshlrev_b64 v[64:65], 13, v[64:65]
	v_max_f32_e32 v56, 0, v56
	v_max_f32_e32 v57, 0, v57
	v_max_f32_e32 v58, 0, v58
	v_max_f32_e32 v59, 0, v59
	v_pk_mul_f32 v[60:61], v[60:61], v[60:61]
	v_pk_mul_f32 v[66:67], v[58:59], v[58:59]
	v_pk_mul_f32 v[58:59], v[56:57], v[56:57]
	v_cvt_pk_bf16_f32 v56, v60, v61
	v_lshl_add_u64 v[60:61], s[20:21], 0, v[64:65]
	v_max_f32_e32 v62, 0, v62
	v_max_f32_e32 v63, 0, v63
	v_lshl_add_u64 v[60:61], v[60:61], 0, s[30:31]
	v_pk_mul_f32 v[62:63], v[62:63], v[62:63]
	v_lshl_add_u64 v[60:61], v[60:61], 0, s[68:69]
	v_max_f32_e32 v52, 0, v52
	v_max_f32_e32 v53, 0, v53
	v_cvt_pk_bf16_f32 v57, v62, v63
	v_cvt_pk_bf16_f32 v58, v58, v59
	v_cvt_pk_bf16_f32 v59, v66, v67
	v_lshl_add_u64 v[60:61], v[60:61], 0, v[120:121]
	v_max_f32_e32 v48, 0, v48
	v_max_f32_e32 v49, 0, v49
	v_max_f32_e32 v50, 0, v50
	v_max_f32_e32 v51, 0, v51
	v_pk_mul_f32 v[52:53], v[52:53], v[52:53]
	global_store_dwordx4 v[60:61], v[56:59], off
	s_nop 1
	v_pk_mul_f32 v[56:57], v[50:51], v[50:51]
	v_pk_mul_f32 v[50:51], v[48:49], v[48:49]
	v_cvt_pk_bf16_f32 v48, v52, v53
	v_lshl_add_u64 v[52:53], s[14:15], 0, v[64:65]
	v_lshl_add_u64 v[52:53], v[52:53], 0, s[30:31]
	v_lshl_add_u64 v[52:53], v[52:53], 0, s[68:69]
	v_max_f32_e32 v54, 0, v54
	v_max_f32_e32 v55, 0, v55
	v_lshl_add_u64 v[52:53], v[52:53], 0, v[120:121]
	v_pk_mul_f32 v[54:55], v[54:55], v[54:55]
	v_add_co_u32_e32 v52, vcc, s11, v52
	v_cvt_pk_bf16_f32 v49, v54, v55
	v_cvt_pk_bf16_f32 v50, v50, v51
	v_cvt_pk_bf16_f32 v51, v56, v57
	v_addc_co_u32_e32 v53, vcc, 0, v53, vcc
	global_store_dwordx4 v[52:53], v[48:51], off offset:256
	s_nop 1
	v_add_u32_e32 v48, 0x90, v140
	v_ashrrev_i32_e32 v49, 31, v48
	v_max_f32_e32 v44, 0, v44
	v_max_f32_e32 v45, 0, v45
	v_lshlrev_b64 v[48:49], 13, v[48:49]
	v_max_f32_e32 v40, 0, v40
	v_max_f32_e32 v41, 0, v41
	v_max_f32_e32 v42, 0, v42
	v_max_f32_e32 v43, 0, v43
	v_pk_mul_f32 v[44:45], v[44:45], v[44:45]
	v_pk_mul_f32 v[50:51], v[42:43], v[42:43]
	v_pk_mul_f32 v[42:43], v[40:41], v[40:41]
	v_cvt_pk_bf16_f32 v40, v44, v45
	v_lshl_add_u64 v[44:45], s[20:21], 0, v[48:49]
	v_max_f32_e32 v46, 0, v46
	v_max_f32_e32 v47, 0, v47
	v_lshl_add_u64 v[44:45], v[44:45], 0, s[30:31]
	v_pk_mul_f32 v[46:47], v[46:47], v[46:47]
	v_lshl_add_u64 v[44:45], v[44:45], 0, s[68:69]
	v_max_f32_e32 v36, 0, v36
	v_max_f32_e32 v37, 0, v37
	v_cvt_pk_bf16_f32 v41, v46, v47
	v_cvt_pk_bf16_f32 v42, v42, v43
	v_cvt_pk_bf16_f32 v43, v50, v51
	v_lshl_add_u64 v[44:45], v[44:45], 0, v[120:121]
	v_max_f32_e32 v32, 0, v32
	v_max_f32_e32 v33, 0, v33
	v_max_f32_e32 v34, 0, v34
	v_max_f32_e32 v35, 0, v35
	v_pk_mul_f32 v[36:37], v[36:37], v[36:37]
	global_store_dwordx4 v[44:45], v[40:43], off
	s_nop 1
	v_pk_mul_f32 v[40:41], v[34:35], v[34:35]
	v_pk_mul_f32 v[34:35], v[32:33], v[32:33]
	v_cvt_pk_bf16_f32 v32, v36, v37
	v_lshl_add_u64 v[36:37], s[14:15], 0, v[48:49]
	v_lshl_add_u64 v[36:37], v[36:37], 0, s[30:31]
	v_lshl_add_u64 v[36:37], v[36:37], 0, s[68:69]
	v_max_f32_e32 v38, 0, v38
	v_max_f32_e32 v39, 0, v39
	v_lshl_add_u64 v[36:37], v[36:37], 0, v[120:121]
	v_pk_mul_f32 v[38:39], v[38:39], v[38:39]
	v_add_co_u32_e32 v36, vcc, s11, v36
	v_cvt_pk_bf16_f32 v33, v38, v39
	v_cvt_pk_bf16_f32 v34, v34, v35
	v_cvt_pk_bf16_f32 v35, v40, v41
	v_addc_co_u32_e32 v37, vcc, 0, v37, vcc
	global_store_dwordx4 v[36:37], v[32:35], off offset:256
	s_nop 1
	v_add_u32_e32 v32, 0xa0, v140
	v_ashrrev_i32_e32 v33, 31, v32
	v_max_f32_e32 v28, 0, v28
	v_max_f32_e32 v29, 0, v29
	v_lshlrev_b64 v[32:33], 13, v[32:33]
	v_max_f32_e32 v24, 0, v24
	v_max_f32_e32 v25, 0, v25
	v_max_f32_e32 v26, 0, v26
	v_max_f32_e32 v27, 0, v27
	v_pk_mul_f32 v[28:29], v[28:29], v[28:29]
	v_pk_mul_f32 v[34:35], v[26:27], v[26:27]
	v_pk_mul_f32 v[26:27], v[24:25], v[24:25]
	v_cvt_pk_bf16_f32 v24, v28, v29
	v_lshl_add_u64 v[28:29], s[20:21], 0, v[32:33]
	v_max_f32_e32 v30, 0, v30
	v_max_f32_e32 v31, 0, v31
	v_lshl_add_u64 v[28:29], v[28:29], 0, s[30:31]
	v_pk_mul_f32 v[30:31], v[30:31], v[30:31]
	v_lshl_add_u64 v[28:29], v[28:29], 0, s[68:69]
	v_max_f32_e32 v20, 0, v20
	v_max_f32_e32 v21, 0, v21
	v_cvt_pk_bf16_f32 v25, v30, v31
	v_cvt_pk_bf16_f32 v26, v26, v27
	v_cvt_pk_bf16_f32 v27, v34, v35
	v_lshl_add_u64 v[28:29], v[28:29], 0, v[120:121]
	v_max_f32_e32 v16, 0, v16
	v_max_f32_e32 v17, 0, v17
	v_max_f32_e32 v18, 0, v18
	v_max_f32_e32 v19, 0, v19
	v_pk_mul_f32 v[20:21], v[20:21], v[20:21]
	global_store_dwordx4 v[28:29], v[24:27], off
	s_nop 1
	v_pk_mul_f32 v[24:25], v[18:19], v[18:19]
	v_pk_mul_f32 v[18:19], v[16:17], v[16:17]
	v_cvt_pk_bf16_f32 v16, v20, v21
	v_lshl_add_u64 v[20:21], s[14:15], 0, v[32:33]
	v_lshl_add_u64 v[20:21], v[20:21], 0, s[30:31]
	v_lshl_add_u64 v[20:21], v[20:21], 0, s[68:69]
	v_max_f32_e32 v22, 0, v22
	v_max_f32_e32 v23, 0, v23
	v_lshl_add_u64 v[20:21], v[20:21], 0, v[120:121]
	v_pk_mul_f32 v[22:23], v[22:23], v[22:23]
	v_add_co_u32_e32 v20, vcc, s11, v20
	v_cvt_pk_bf16_f32 v17, v22, v23
	v_cvt_pk_bf16_f32 v18, v18, v19
	v_cvt_pk_bf16_f32 v19, v24, v25
	v_addc_co_u32_e32 v21, vcc, 0, v21, vcc
	global_store_dwordx4 v[20:21], v[16:19], off offset:256
	s_nop 1
	v_add_u32_e32 v16, 0xb0, v140
	v_ashrrev_i32_e32 v17, 31, v16
	v_max_f32_e32 v12, 0, v12
	v_max_f32_e32 v13, 0, v13
	v_lshlrev_b64 v[16:17], 13, v[16:17]
	v_max_f32_e32 v8, 0, v8
	v_max_f32_e32 v9, 0, v9
	v_max_f32_e32 v10, 0, v10
	v_max_f32_e32 v11, 0, v11
	v_pk_mul_f32 v[12:13], v[12:13], v[12:13]
	v_pk_mul_f32 v[18:19], v[10:11], v[10:11]
	v_pk_mul_f32 v[10:11], v[8:9], v[8:9]
	v_cvt_pk_bf16_f32 v8, v12, v13
	v_lshl_add_u64 v[12:13], s[20:21], 0, v[16:17]
	v_max_f32_e32 v14, 0, v14
	v_max_f32_e32 v15, 0, v15
	v_lshl_add_u64 v[12:13], v[12:13], 0, s[30:31]
	v_pk_mul_f32 v[14:15], v[14:15], v[14:15]
	v_lshl_add_u64 v[12:13], v[12:13], 0, s[68:69]
	v_max_f32_e32 v4, 0, v4
	v_max_f32_e32 v5, 0, v5
	v_cvt_pk_bf16_f32 v9, v14, v15
	v_cvt_pk_bf16_f32 v10, v10, v11
	v_cvt_pk_bf16_f32 v11, v18, v19
	v_lshl_add_u64 v[12:13], v[12:13], 0, v[120:121]
	v_max_f32_e32 v0, 0, v0
	v_max_f32_e32 v1, 0, v1
	v_max_f32_e32 v2, 0, v2
	v_max_f32_e32 v3, 0, v3
	v_pk_mul_f32 v[4:5], v[4:5], v[4:5]
	global_store_dwordx4 v[12:13], v[8:11], off
	s_nop 1
	v_pk_mul_f32 v[8:9], v[2:3], v[2:3]
	v_pk_mul_f32 v[2:3], v[0:1], v[0:1]
	v_cvt_pk_bf16_f32 v0, v4, v5
	v_lshl_add_u64 v[4:5], s[14:15], 0, v[16:17]
	v_lshl_add_u64 v[4:5], v[4:5], 0, s[30:31]
	v_lshl_add_u64 v[4:5], v[4:5], 0, s[68:69]
	v_lshl_add_u64 v[4:5], v[4:5], 0, v[120:121]
	v_max_f32_e32 v6, 0, v6
	v_max_f32_e32 v7, 0, v7
	v_add_co_u32_e32 v4, vcc, 0x7000000, v4
	v_pk_mul_f32 v[6:7], v[6:7], v[6:7]
	s_nop 0
	v_addc_co_u32_e32 v5, vcc, 0, v5, vcc
	v_cvt_pk_bf16_f32 v1, v6, v7
	v_cvt_pk_bf16_f32 v2, v2, v3
	v_cvt_pk_bf16_f32 v3, v8, v9
	s_andn2_b64 vcc, exec, s[48:49]
	s_mov_b64 s[30:31], -1
	global_store_dwordx4 v[4:5], v[0:3], off offset:256
	s_cbranch_vccnz .LBB0_1758
	s_andn2_b64 vcc, exec, s[16:17]
	s_cbranch_vccnz .LBB0_1757
	s_barrier
	s_branch .LBB0_1757
